# stack5 + diff-attention first-step QK phase: eight lgkmcnt waits that the closing lgkmcnt(0) before the loop-back barrier already covers removed (the second step has none)
# speedup vs baseline: 1.0100x; 1.0052x over previous
.LBB0_280:
	v_mfma_f32_32x32x16_bf16 v[144:159], v[220:223], v[184:187], v[80:95]
	v_add_f32_e32 v2, v112, v113
	v_add_f32_e32 v2, v114, v2
	v_add_f32_e32 v2, v115, v2
	s_lshl_b32 s72, s72, 1
	v_add_f32_e32 v2, v116, v2
	v_add_u32_e32 v0, s72, v245
	v_add_f32_e32 v2, v117, v2
	v_cvt_pk_bf16_f32 v188, v112, v113
	v_cvt_pk_bf16_f32 v189, v114, v115
	v_mfma_f32_32x32x16_bf16 v[128:143], v[212:215], v[184:187], v[80:95]
	v_add_f32_e32 v2, v118, v2
	v_add_f32_e32 v2, v119, v2
	v_add_f32_e32 v2, v120, v2
	v_add_f32_e32 v2, v121, v2
	v_cvt_pk_bf16_f32 v190, v116, v117
	v_cvt_pk_bf16_f32 v191, v118, v119
	v_mfma_f32_32x32x16_bf16 v[144:159], v[216:219], v[176:179], v[144:159]
	v_add_f32_e32 v2, v122, v2
	v_add_f32_e32 v2, v123, v2
	v_add_f32_e32 v2, v124, v2
	v_add_f32_e32 v2, v125, v2
	v_cvt_pk_bf16_f32 v180, v120, v121
	v_cvt_pk_bf16_f32 v181, v122, v123
	v_mfma_f32_32x32x16_bf16 v[128:143], v[204:207], v[176:179], v[128:143]
	v_add_f32_e32 v2, v126, v2
	v_add_f32_e32 v2, v127, v2
	v_add_f32_e32 v2, v96, v2
	v_add_f32_e32 v2, v97, v2
	v_cvt_pk_bf16_f32 v182, v124, v125
	v_cvt_pk_bf16_f32 v183, v126, v127
	v_mfma_f32_32x32x16_bf16 v[144:159], v[208:211], v[172:175], v[144:159]
	v_add_f32_e32 v2, v98, v2
	v_add_f32_e32 v2, v99, v2
	v_add_f32_e32 v2, v100, v2
	v_add_f32_e32 v2, v101, v2
	v_cvt_pk_bf16_f32 v168, v96, v97
	v_cvt_pk_bf16_f32 v169, v98, v99
	v_mfma_f32_32x32x16_bf16 v[128:143], v[200:203], v[172:175], v[128:143]
	v_add_f32_e32 v2, v102, v2
	v_add_f32_e32 v2, v103, v2
	v_add_f32_e32 v2, v104, v2
	v_add_f32_e32 v6, v105, v2
	v_cvt_pk_bf16_f32 v170, v100, v101
	v_cvt_pk_bf16_f32 v171, v102, v103
	ds_read_b64_tr_b16 v[2:3], v0 offset:24576
	ds_read_b64_tr_b16 v[4:5], v0 offset:25088
	v_mfma_f32_32x32x16_bf16 v[144:159], v[196:199], v[164:167], v[144:159]
	v_add_f32_e32 v6, v106, v6
	v_add_f32_e32 v6, v107, v6
	v_add_f32_e32 v6, v108, v6
	v_add_f32_e32 v10, v109, v6
	v_cvt_pk_bf16_f32 v160, v104, v105
	v_cvt_pk_bf16_f32 v161, v106, v107
	ds_read_b64_tr_b16 v[6:7], v0 offset:28672
	ds_read_b64_tr_b16 v[8:9], v0 offset:29184
	v_mfma_f32_32x32x16_bf16 v[128:143], v[192:195], v[164:167], v[128:143]
	ds_read_b64_tr_b16 v[100:101], v0 offset:32768
	ds_read_b64_tr_b16 v[102:103], v0 offset:33280
	ds_read_b64_tr_b16 v[104:105], v0 offset:36864
	ds_read_b64_tr_b16 v[106:107], v0 offset:37376
	ds_read_b64_tr_b16 v[112:113], v0 offset:25600
	ds_read_b64_tr_b16 v[114:115], v0 offset:26112
	ds_read_b64_tr_b16 v[116:117], v0 offset:29696
	ds_read_b64_tr_b16 v[118:119], v0 offset:30208
	v_add_f32_e32 v10, v110, v10
	v_add_f32_e32 v10, v111, v10
	v_add_f32_e32 v12, 0, v10
	v_cvt_pk_bf16_f32 v162, v108, v109
	v_cvt_pk_bf16_f32 v163, v110, v111
	v_lshl_add_u64 v[14:15], v[234:235], 0, s[6:7]
	v_lshl_add_u64 v[10:11], v[14:15], 0, s[56:57]
	s_add_i32 s72, s78, s64
	v_lshl_add_u64 v[208:209], v[236:237], 0, s[6:7]
	s_mov_b32 s73, m0
	s_mov_b32 m0, s72
	s_nop 0
	global_load_lds_dwordx4 v[10:11], off
	s_mov_b32 m0, s73
	v_lshl_add_u64 v[10:11], v[208:209], 0, s[48:49]
	s_lshl_b32 s72, s76, 1
	v_lshl_add_u64 v[210:211], v[238:239], 0, s[6:7]
	s_add_i32 s72, s72, s63
	s_mov_b32 s73, m0
	s_mov_b32 m0, s72
	s_nop 0
	global_load_lds_dwordx4 v[10:11], off
	s_mov_b32 m0, s73
	v_lshl_add_u64 v[10:11], v[210:211], 0, s[48:49]
	s_addk_i32 s72, 0x2000
	s_mov_b32 s73, m0
	s_mov_b32 m0, s72
	s_nop 0
	global_load_lds_dwordx4 v[10:11], off
	s_mov_b32 m0, s73
	v_max_f32_e32 v10, v145, v145
	v_max_f32_e32 v11, v144, v144
	v_max_f32_e32 v10, v11, v10
	v_max3_f32 v11, v146, v147, v129
	v_max3_f32 v10, v10, v128, v130
	v_max3_f32 v10, v10, v131, v148
	v_max3_f32 v11, v11, v150, v151
	v_max3_f32 v10, v10, v149, v132
	v_max3_f32 v11, v11, v134, v135
	v_max3_f32 v10, v10, v133, v152
	v_max3_f32 v11, v11, v154, v155
	v_max3_f32 v10, v10, v153, v136
	v_max3_f32 v11, v11, v138, v139
	v_max3_f32 v10, v10, v137, v156
	v_max3_f32 v11, v11, v158, v159
	v_max3_f32 v10, v10, v157, v140
	v_max3_f32 v11, v11, v142, v143
	v_max3_f32 v10, v10, v141, v11
	v_mov_b32_e32 v11, v10
	s_nop 1
	v_permlane32_swap_b32_e32 v10, v11
	v_max_f32_e32 v11, v11, v11
	v_max_f32_e32 v10, v10, v10
	v_max_f32_e32 v10, v10, v11
	v_cmp_lt_f32_e32 vcc, s96, v10
	s_cmp_lg_u64 vcc, 0
	v_add_f32_e32 v212, v231, v12
	s_cselect_b64 s[72:73], -1, 0
	s_cbranch_vccnz .LBB0_288
